# k12
# baseline (speedup 1.0000x reference)
; #define XS(s_) (ldbf4(XB + (size_t)(tokbase + (s_)) * D + col) * rsl[(s_) - tb0 + 8])
; __global__ void __launch_bounds__(NTHREADS, 2) mega_fwd(Params p) {
;     ...
;                     int lo = t - hw < 0 ? 0 : t - hw, hi2 = t + hw - 1 > T - 1 ? T - 1 : t + hw - 1;
;                     f32x4 sum = {0.f, 0.f, 0.f, 0.f};
; #pragma unroll
;                     for (int s2 = 0; s2 < 16; ++s2) if (lo + s2 <= hi2) sum += XS(lo + s2);
.LBB0_587:
	s_or_b64 exec, exec, s[8:9]
	v_add_u32_e32 v0, s16, v15
	v_sub_u32_e32 v2, v0, v14
	v_max_i32_e32 v21, 0, v2
	v_or_b32_e32 v0, v0, v14
	v_mov_b32_e32 v2, v1
	v_mov_b32_e32 v3, v1
	v_min_i32_e32 v22, 0x800, v0
	v_mov_b32_e32 v0, v1
	v_mov_b64_e32 v[4:5], v[2:3]
	v_cmp_lt_i32_e32 vcc, v21, v22
	v_mov_b64_e32 v[2:3], v[0:1]
	s_waitcnt lgkmcnt(0)
	s_barrier
	v_add_u32_e32 v38, s18, v21
	v_subrev_u32_e32 v39, s16, v21
	v_lshl_add_u32 v39, v39, 2, s2
	v_mov_b32_e32 v40, v38
	v_ashrrev_i32_e32 v41, 31, v40
	v_lshlrev_b64 v[40:41], 11, v[40:41]
	v_lshl_add_u64 v[40:41], v[6:7], 0, v[40:41]
	global_load_dwordx2 v[50:51], v[40:41], off
	v_add_u32_e32 v40, 1, v38
	v_ashrrev_i32_e32 v41, 31, v40
	v_lshlrev_b64 v[40:41], 11, v[40:41]
	v_lshl_add_u64 v[40:41], v[6:7], 0, v[40:41]
	global_load_dwordx2 v[52:53], v[40:41], off
	v_add_u32_e32 v40, 2, v38
	v_ashrrev_i32_e32 v41, 31, v40
	v_lshlrev_b64 v[40:41], 11, v[40:41]
	v_lshl_add_u64 v[40:41], v[6:7], 0, v[40:41]
	global_load_dwordx2 v[54:55], v[40:41], off
	v_add_u32_e32 v40, 3, v38
	v_ashrrev_i32_e32 v41, 31, v40
	v_lshlrev_b64 v[40:41], 11, v[40:41]
	v_lshl_add_u64 v[40:41], v[6:7], 0, v[40:41]
	global_load_dwordx2 v[56:57], v[40:41], off
	v_add_u32_e32 v40, 4, v38
	v_ashrrev_i32_e32 v41, 31, v40
	v_lshlrev_b64 v[40:41], 11, v[40:41]
	v_lshl_add_u64 v[40:41], v[6:7], 0, v[40:41]
	global_load_dwordx2 v[58:59], v[40:41], off
	v_add_u32_e32 v40, 5, v38
	v_ashrrev_i32_e32 v41, 31, v40
	v_lshlrev_b64 v[40:41], 11, v[40:41]
	v_lshl_add_u64 v[40:41], v[6:7], 0, v[40:41]
	global_load_dwordx2 v[60:61], v[40:41], off
	v_add_u32_e32 v40, 6, v38
	v_ashrrev_i32_e32 v41, 31, v40
	v_lshlrev_b64 v[40:41], 11, v[40:41]
	v_lshl_add_u64 v[40:41], v[6:7], 0, v[40:41]
	global_load_dwordx2 v[62:63], v[40:41], off
	v_add_u32_e32 v40, 7, v38
	v_ashrrev_i32_e32 v41, 31, v40
	v_lshlrev_b64 v[40:41], 11, v[40:41]
	v_lshl_add_u64 v[40:41], v[6:7], 0, v[40:41]
	global_load_dwordx2 v[64:65], v[40:41], off
	v_add_u32_e32 v40, 8, v38
	v_ashrrev_i32_e32 v41, 31, v40
	v_lshlrev_b64 v[40:41], 11, v[40:41]
	v_lshl_add_u64 v[40:41], v[6:7], 0, v[40:41]
	global_load_dwordx2 v[66:67], v[40:41], off
	v_add_u32_e32 v40, 9, v38
	v_ashrrev_i32_e32 v41, 31, v40
	v_lshlrev_b64 v[40:41], 11, v[40:41]
	v_lshl_add_u64 v[40:41], v[6:7], 0, v[40:41]
	global_load_dwordx2 v[68:69], v[40:41], off
	v_add_u32_e32 v40, 10, v38
	v_ashrrev_i32_e32 v41, 31, v40
	v_lshlrev_b64 v[40:41], 11, v[40:41]
	v_lshl_add_u64 v[40:41], v[6:7], 0, v[40:41]
	global_load_dwordx2 v[70:71], v[40:41], off
	v_add_u32_e32 v40, 11, v38
	v_ashrrev_i32_e32 v41, 31, v40
	v_lshlrev_b64 v[40:41], 11, v[40:41]
	v_lshl_add_u64 v[40:41], v[6:7], 0, v[40:41]
	global_load_dwordx2 v[72:73], v[40:41], off
	v_add_u32_e32 v40, 12, v38
	v_ashrrev_i32_e32 v41, 31, v40
	v_lshlrev_b64 v[40:41], 11, v[40:41]
	v_lshl_add_u64 v[40:41], v[6:7], 0, v[40:41]
	global_load_dwordx2 v[74:75], v[40:41], off
	v_add_u32_e32 v40, 13, v38
	v_ashrrev_i32_e32 v41, 31, v40
	v_lshlrev_b64 v[40:41], 11, v[40:41]
	v_lshl_add_u64 v[40:41], v[6:7], 0, v[40:41]
	global_load_dwordx2 v[76:77], v[40:41], off
	v_add_u32_e32 v40, 14, v38
	v_ashrrev_i32_e32 v41, 31, v40
	v_lshlrev_b64 v[40:41], 11, v[40:41]
	v_lshl_add_u64 v[40:41], v[6:7], 0, v[40:41]
	global_load_dwordx2 v[78:79], v[40:41], off
	v_add_u32_e32 v40, 15, v38
	v_ashrrev_i32_e32 v41, 31, v40
	v_lshlrev_b64 v[40:41], 11, v[40:41]
	v_lshl_add_u64 v[40:41], v[6:7], 0, v[40:41]
	global_load_dwordx2 v[80:81], v[40:41], off
	ds_read_b32 v82, v39 offset:32
	ds_read_b32 v84, v39 offset:36
	ds_read_b32 v86, v39 offset:40
	ds_read_b32 v88, v39 offset:44
	ds_read_b32 v90, v39 offset:48
	ds_read_b32 v92, v39 offset:52
	ds_read_b32 v94, v39 offset:56
	ds_read_b32 v96, v39 offset:60
	ds_read_b32 v98, v39 offset:64
	ds_read_b32 v100, v39 offset:68
	ds_read_b32 v102, v39 offset:72
	ds_read_b32 v104, v39 offset:76
	ds_read_b32 v106, v39 offset:80
	ds_read_b32 v108, v39 offset:84
	ds_read_b32 v110, v39 offset:88
	ds_read_b32 v112, v39 offset:92
	v_mov_b32_e32 v0, v21
	v_cmp_lt_i32_e32 vcc, v0, v22
	s_and_saveexec_b64 s[8:9], vcc
	s_cbranch_execz .Lpw_0
	s_waitcnt vmcnt(15)
	v_lshlrev_b32_e32 v24, 16, v50
	v_and_b32_e32 v25, 0xffff0000, v50
	v_lshlrev_b32_e32 v10, 16, v51
	v_and_b32_e32 v11, 0xffff0000, v51
	s_waitcnt lgkmcnt(15)
	v_pk_fma_f32 v[4:5], v[82:83], v[10:11], v[4:5] op_sel_hi:[0,1,1]
	v_pk_fma_f32 v[2:3], v[82:83], v[24:25], v[2:3] op_sel_hi:[0,1,1]
.Lpw_0:
	s_or_b64 exec, exec, s[8:9]
	v_add_u32_e32 v0, 1, v21
	v_cmp_lt_i32_e32 vcc, v0, v22
	s_and_saveexec_b64 s[8:9], vcc
	s_cbranch_execz .Lpw_1
	s_waitcnt vmcnt(14)
	v_lshlrev_b32_e32 v24, 16, v52
	v_and_b32_e32 v25, 0xffff0000, v52
	v_lshlrev_b32_e32 v10, 16, v53
	v_and_b32_e32 v11, 0xffff0000, v53
	s_waitcnt lgkmcnt(14)
	v_pk_fma_f32 v[4:5], v[84:85], v[10:11], v[4:5] op_sel_hi:[0,1,1]
	v_pk_fma_f32 v[2:3], v[84:85], v[24:25], v[2:3] op_sel_hi:[0,1,1]
.Lpw_1:
	s_or_b64 exec, exec, s[8:9]
	v_add_u32_e32 v0, 2, v21
	v_cmp_lt_i32_e32 vcc, v0, v22
	s_and_saveexec_b64 s[8:9], vcc
	s_cbranch_execz .Lpw_2
	s_waitcnt vmcnt(13)
	v_lshlrev_b32_e32 v24, 16, v54
	v_and_b32_e32 v25, 0xffff0000, v54
	v_lshlrev_b32_e32 v10, 16, v55
	v_and_b32_e32 v11, 0xffff0000, v55
	s_waitcnt lgkmcnt(13)
	v_pk_fma_f32 v[4:5], v[86:87], v[10:11], v[4:5] op_sel_hi:[0,1,1]
	v_pk_fma_f32 v[2:3], v[86:87], v[24:25], v[2:3] op_sel_hi:[0,1,1]
.Lpw_2:
	s_or_b64 exec, exec, s[8:9]
	v_add_u32_e32 v0, 3, v21
	v_cmp_lt_i32_e32 vcc, v0, v22
	s_and_saveexec_b64 s[8:9], vcc
	s_cbranch_execz .Lpw_3
	s_waitcnt vmcnt(12)
	v_lshlrev_b32_e32 v24, 16, v56
	v_and_b32_e32 v25, 0xffff0000, v56
	v_lshlrev_b32_e32 v10, 16, v57
	v_and_b32_e32 v11, 0xffff0000, v57
	s_waitcnt lgkmcnt(12)
	v_pk_fma_f32 v[4:5], v[88:89], v[10:11], v[4:5] op_sel_hi:[0,1,1]
	v_pk_fma_f32 v[2:3], v[88:89], v[24:25], v[2:3] op_sel_hi:[0,1,1]
; #define XS(s_) (ldbf4(XB + (size_t)(tokbase + (s_)) * D + col) * rsl[(s_) - tb0 + 8])
; __global__ void __launch_bounds__(NTHREADS, 2) mega_fwd(Params p) {
;     ...
;                     int lo = t - hw < 0 ? 0 : t - hw, hi2 = t + hw - 1 > T - 1 ? T - 1 : t + hw - 1;
;                     f32x4 sum = {0.f, 0.f, 0.f, 0.f};
; #pragma unroll
;                     for (int s2 = 0; s2 < 16; ++s2) if (lo + s2 <= hi2) sum += XS(lo + s2);
.Lpw_3:
	s_or_b64 exec, exec, s[8:9]
	v_add_u32_e32 v0, 4, v21
	v_cmp_lt_i32_e32 vcc, v0, v22
	s_and_saveexec_b64 s[8:9], vcc
	s_cbranch_execz .Lpw_4
	s_waitcnt vmcnt(11)
	v_lshlrev_b32_e32 v24, 16, v58
	v_and_b32_e32 v25, 0xffff0000, v58
	v_lshlrev_b32_e32 v10, 16, v59
	v_and_b32_e32 v11, 0xffff0000, v59
	s_waitcnt lgkmcnt(11)
	v_pk_fma_f32 v[4:5], v[90:91], v[10:11], v[4:5] op_sel_hi:[0,1,1]
	v_pk_fma_f32 v[2:3], v[90:91], v[24:25], v[2:3] op_sel_hi:[0,1,1]
.Lpw_4:
	s_or_b64 exec, exec, s[8:9]
	v_add_u32_e32 v0, 5, v21
	v_cmp_lt_i32_e32 vcc, v0, v22
	s_and_saveexec_b64 s[8:9], vcc
	s_cbranch_execz .Lpw_5
	s_waitcnt vmcnt(10)
	v_lshlrev_b32_e32 v24, 16, v60
	v_and_b32_e32 v25, 0xffff0000, v60
	v_lshlrev_b32_e32 v10, 16, v61
	v_and_b32_e32 v11, 0xffff0000, v61
	s_waitcnt lgkmcnt(10)
	v_pk_fma_f32 v[4:5], v[92:93], v[10:11], v[4:5] op_sel_hi:[0,1,1]
	v_pk_fma_f32 v[2:3], v[92:93], v[24:25], v[2:3] op_sel_hi:[0,1,1]
.Lpw_5:
	s_or_b64 exec, exec, s[8:9]
	v_add_u32_e32 v0, 6, v21
	v_cmp_lt_i32_e32 vcc, v0, v22
	s_and_saveexec_b64 s[8:9], vcc
	s_cbranch_execz .Lpw_6
	s_waitcnt vmcnt(9)
	v_lshlrev_b32_e32 v24, 16, v62
	v_and_b32_e32 v25, 0xffff0000, v62
	v_lshlrev_b32_e32 v10, 16, v63
	v_and_b32_e32 v11, 0xffff0000, v63
	s_waitcnt lgkmcnt(9)
	v_pk_fma_f32 v[4:5], v[94:95], v[10:11], v[4:5] op_sel_hi:[0,1,1]
	v_pk_fma_f32 v[2:3], v[94:95], v[24:25], v[2:3] op_sel_hi:[0,1,1]
.Lpw_6:
	s_or_b64 exec, exec, s[8:9]
	v_add_u32_e32 v0, 7, v21
	v_cmp_lt_i32_e32 vcc, v0, v22
	s_and_saveexec_b64 s[8:9], vcc
	s_cbranch_execz .Lpw_7
	s_waitcnt vmcnt(8)
	v_lshlrev_b32_e32 v24, 16, v64
	v_and_b32_e32 v25, 0xffff0000, v64
	v_lshlrev_b32_e32 v10, 16, v65
	v_and_b32_e32 v11, 0xffff0000, v65
	s_waitcnt lgkmcnt(8)
	v_pk_fma_f32 v[4:5], v[96:97], v[10:11], v[4:5] op_sel_hi:[0,1,1]
	v_pk_fma_f32 v[2:3], v[96:97], v[24:25], v[2:3] op_sel_hi:[0,1,1]
.Lpw_7:
	s_or_b64 exec, exec, s[8:9]
	v_add_u32_e32 v0, 8, v21
	v_cmp_lt_i32_e32 vcc, v0, v22
	s_and_saveexec_b64 s[8:9], vcc
	s_cbranch_execz .Lpw_8
	s_waitcnt vmcnt(7)
	v_lshlrev_b32_e32 v24, 16, v66
	v_and_b32_e32 v25, 0xffff0000, v66
	v_lshlrev_b32_e32 v10, 16, v67
	v_and_b32_e32 v11, 0xffff0000, v67
	s_waitcnt lgkmcnt(7)
	v_pk_fma_f32 v[4:5], v[98:99], v[10:11], v[4:5] op_sel_hi:[0,1,1]
	v_pk_fma_f32 v[2:3], v[98:99], v[24:25], v[2:3] op_sel_hi:[0,1,1]
.Lpw_8:
	s_or_b64 exec, exec, s[8:9]
	v_add_u32_e32 v0, 9, v21
	v_cmp_lt_i32_e32 vcc, v0, v22
	s_and_saveexec_b64 s[8:9], vcc
	s_cbranch_execz .Lpw_9
	s_waitcnt vmcnt(6)
	v_lshlrev_b32_e32 v24, 16, v68
	v_and_b32_e32 v25, 0xffff0000, v68
	v_lshlrev_b32_e32 v10, 16, v69
	v_and_b32_e32 v11, 0xffff0000, v69
	s_waitcnt lgkmcnt(6)
	v_pk_fma_f32 v[4:5], v[100:101], v[10:11], v[4:5] op_sel_hi:[0,1,1]
	v_pk_fma_f32 v[2:3], v[100:101], v[24:25], v[2:3] op_sel_hi:[0,1,1]
.Lpw_9:
	s_or_b64 exec, exec, s[8:9]
	v_add_u32_e32 v0, 10, v21
	v_cmp_lt_i32_e32 vcc, v0, v22
	s_and_saveexec_b64 s[8:9], vcc
	s_cbranch_execz .Lpw_10
	s_waitcnt vmcnt(5)
	v_lshlrev_b32_e32 v24, 16, v70
	v_and_b32_e32 v25, 0xffff0000, v70
	v_lshlrev_b32_e32 v10, 16, v71
	v_and_b32_e32 v11, 0xffff0000, v71
	s_waitcnt lgkmcnt(5)
	v_pk_fma_f32 v[4:5], v[102:103], v[10:11], v[4:5] op_sel_hi:[0,1,1]
	v_pk_fma_f32 v[2:3], v[102:103], v[24:25], v[2:3] op_sel_hi:[0,1,1]
.Lpw_10:
	s_or_b64 exec, exec, s[8:9]
	v_add_u32_e32 v0, 11, v21
	v_cmp_lt_i32_e32 vcc, v0, v22
	s_and_saveexec_b64 s[8:9], vcc
	s_cbranch_execz .Lpw_11
	s_waitcnt vmcnt(4)
	v_lshlrev_b32_e32 v24, 16, v72
	v_and_b32_e32 v25, 0xffff0000, v72
	v_lshlrev_b32_e32 v10, 16, v73
	v_and_b32_e32 v11, 0xffff0000, v73
	s_waitcnt lgkmcnt(4)
	v_pk_fma_f32 v[4:5], v[104:105], v[10:11], v[4:5] op_sel_hi:[0,1,1]
	v_pk_fma_f32 v[2:3], v[104:105], v[24:25], v[2:3] op_sel_hi:[0,1,1]
.Lpw_11:
	s_or_b64 exec, exec, s[8:9]
	v_add_u32_e32 v0, 12, v21
	v_cmp_lt_i32_e32 vcc, v0, v22
	s_and_saveexec_b64 s[8:9], vcc
	s_cbranch_execz .Lpw_12
	s_waitcnt vmcnt(3)
	v_lshlrev_b32_e32 v24, 16, v74
	v_and_b32_e32 v25, 0xffff0000, v74
	v_lshlrev_b32_e32 v10, 16, v75
	v_and_b32_e32 v11, 0xffff0000, v75
	s_waitcnt lgkmcnt(3)
	v_pk_fma_f32 v[4:5], v[106:107], v[10:11], v[4:5] op_sel_hi:[0,1,1]
	v_pk_fma_f32 v[2:3], v[106:107], v[24:25], v[2:3] op_sel_hi:[0,1,1]
.Lpw_12:
	s_or_b64 exec, exec, s[8:9]
	v_add_u32_e32 v0, 13, v21
	v_cmp_lt_i32_e32 vcc, v0, v22
	s_and_saveexec_b64 s[8:9], vcc
	s_cbranch_execz .Lpw_13
	s_waitcnt vmcnt(2)
	v_lshlrev_b32_e32 v24, 16, v76
	v_and_b32_e32 v25, 0xffff0000, v76
	v_lshlrev_b32_e32 v10, 16, v77
	v_and_b32_e32 v11, 0xffff0000, v77
	s_waitcnt lgkmcnt(2)
	v_pk_fma_f32 v[4:5], v[108:109], v[10:11], v[4:5] op_sel_hi:[0,1,1]
	v_pk_fma_f32 v[2:3], v[108:109], v[24:25], v[2:3] op_sel_hi:[0,1,1]
.Lpw_13:
	s_or_b64 exec, exec, s[8:9]
	v_add_u32_e32 v0, 14, v21
	v_cmp_lt_i32_e32 vcc, v0, v22
	s_and_saveexec_b64 s[8:9], vcc
	s_cbranch_execz .Lpw_14
	s_waitcnt vmcnt(1)
	v_lshlrev_b32_e32 v24, 16, v78
	v_and_b32_e32 v25, 0xffff0000, v78
	v_lshlrev_b32_e32 v10, 16, v79
	v_and_b32_e32 v11, 0xffff0000, v79
	s_waitcnt lgkmcnt(1)
	v_pk_fma_f32 v[4:5], v[110:111], v[10:11], v[4:5] op_sel_hi:[0,1,1]
	v_pk_fma_f32 v[2:3], v[110:111], v[24:25], v[2:3] op_sel_hi:[0,1,1]
.Lpw_14:
	s_or_b64 exec, exec, s[8:9]
	v_add_u32_e32 v0, 15, v21
	v_cmp_lt_i32_e32 vcc, v0, v22
	s_and_saveexec_b64 s[8:9], vcc
	s_cbranch_execz .Lpw_15
	s_waitcnt vmcnt(0)
	v_lshlrev_b32_e32 v24, 16, v80
	v_and_b32_e32 v25, 0xffff0000, v80
	v_lshlrev_b32_e32 v10, 16, v81
	v_and_b32_e32 v11, 0xffff0000, v81
	s_waitcnt lgkmcnt(0)
	v_pk_fma_f32 v[4:5], v[112:113], v[10:11], v[4:5] op_sel_hi:[0,1,1]
	v_pk_fma_f32 v[2:3], v[112:113], v[24:25], v[2:3] op_sel_hi:[0,1,1]
.Lpw_15:
	s_or_b64 exec, exec, s[8:9]
	s_waitcnt vmcnt(0) lgkmcnt(0)
	s_and_b32 s8, s3, 0xfffff800
	s_and_b32 s9, s3, 0x7c0
	s_or_b32 s10, s9, s8
	v_add_u32_e32 v10, s10, v15
	v_ashrrev_i32_e32 v11, 31, v10
	v_lshlrev_b64 v[10:11], 11, v[10:11]
	v_add_u32_e32 v0, s9, v17
	v_add_u32_e32 v24, s9, v20
	v_lshl_add_u64 v[10:11], v[8:9], 0, v[10:11]
	v_add_u32_e32 v23, s8, v0
	v_add_u32_e32 v25, s8, v24
	v_add_u32_e32 v26, -1, v22
	s_mov_b32 s10, 0
	v_mov_b32_e32 v22, v16
	s_branch .LBB0_621

; __device__ __forceinline__ int lane_id_asm() { int l; asm volatile("v_mbcnt_lo_u32_b32 %0, -1, 0\n\tv_mbcnt_hi_u32_b32 %0, -1, %0" : "=v"(l)); return l; }
; __global__ void __launch_bounds__(NTHREADS, 2) mega_fwd(Params p) {
;     ...
;                     const unsigned* km = (const unsigned*)(ws + WS_KMAX) + ((b * 8 + h) * 2) * 2;
;                     const float kb2a = __uint_as_float(__hip_atomic_load(km + 0, __ATOMIC_RELAXED, __HIP_MEMORY_SCOPE_AGENT)) + __uint_as_float(__hip_atomic_load(km + 1, __ATOMIC_RELAXED, __HIP_MEMORY_SCOPE_AGENT));
;                     const float kb2b = __uint_as_float(__hip_atomic_load(km + 2, __ATOMIC_RELAXED, __HIP_MEMORY_SCOPE_AGENT)) + __uint_as_float(__hip_atomic_load(km + 3, __ATOMIC_RELAXED, __HIP_MEMORY_SCOPE_AGENT));
;                     bool okref;
;                     { const int hiq = lane_id_asm() >> 5; float qa = 0.f, qbb = 0.f;
; #pragma unroll
;                         for (int d0 = 0; d0 < 4; ++d0) { const u32x4 ra = *(const u32x4*)(qrow + d0 * 16 + hiq * 8), rb = *(const u32x4*)(qrow + 64 + d0 * 16 + hiq * 8);
; #pragma unroll
;                             for (int e = 0; e < 4; ++e) { const float a0 = __uint_as_float(ra[e] << 16), a1 = __uint_as_float(ra[e] & 0xffff0000u), b0 = __uint_as_float(rb[e] << 16), b1 = __uint_as_float(rb[e] & 0xffff0000u);
;                                 qa += a0 * a0 + a1 * a1; qbb += b0 * b0 + b1 * b1; } }
.LBB0_1324:
	s_ashr_i32 s4, s83, 8
	s_lshl_b32 s5, s83, 2
	s_lshr_b32 s2, s83, 3
	s_lshl_b32 s3, s4, 5
	s_and_b32 s6, s5, 24
	s_or_b32 s3, s3, s6
	s_bfe_u32 s6, s83, 0x20006
	s_add_i32 s5, s4, s5
	s_add_i32 s2, s2, s4
	s_add_i32 s5, s5, s6
	s_and_b32 s2, s2, 7
	s_and_b32 s5, s5, 7
	s_lshl_b32 s4, s3, 8
	s_lshl_b32 s84, s2, 8
	s_or_b32 s43, s4, s84
	s_or_b32 s6, s5, s3
	v_mbcnt_lo_u32_b32 v0, -1, 0
	v_mbcnt_hi_u32_b32 v0, -1, v0
	s_add_i32 s43, s43, s86
	v_and_b32_e32 v176, 31, v0
	s_lshl_b32 s6, s6, 2
	v_or_b32_e32 v2, s43, v176
	s_ashr_i32 s7, s6, 31
	v_ashrrev_i32_e32 v3, 31, v2
	s_lshl_b32 s16, s5, 8
	s_lshl_b64 s[6:7], s[6:7], 2
	v_lshlrev_b64 v[2:3], 11, v[2:3]
	s_add_u32 s6, s81, s6
	v_lshl_add_u64 v[2:3], s[38:39], 0, v[2:3]
	s_addc_u32 s7, s82, s7
	v_lshl_add_u64 v[212:213], v[2:3], 0, s[16:17]
	global_load_dword v0, v1, s[6:7] sc1
	global_load_dword v10, v1, s[6:7] offset:4 sc1
	global_load_dword v11, v1, s[6:7] offset:8 sc1
	global_load_dword v12, v1, s[6:7] offset:12 sc1
	v_mbcnt_lo_u32_b32 v2, -1, 0
	v_mbcnt_hi_u32_b32 v2, -1, v2
	v_ashrrev_i32_e32 v2, 2, v2
	v_and_b32_e32 v2, -8, v2
	v_ashrrev_i32_e32 v3, 31, v2
	v_lshl_add_u64 v[6:7], v[2:3], 1, v[212:213]
	global_load_dwordx4 v[2:5], v[6:7], off
	global_load_dwordx4 v[14:17], v[6:7], off offset:128
	global_load_dwordx4 v[100:103], v[6:7], off offset:32
	global_load_dwordx4 v[104:107], v[6:7], off offset:160
	global_load_dwordx4 v[108:111], v[6:7], off offset:64
	global_load_dwordx4 v[112:115], v[6:7], off offset:192
	global_load_dwordx4 v[116:119], v[6:7], off offset:96
	global_load_dwordx4 v[120:123], v[6:7], off offset:224
	s_waitcnt vmcnt(8)
	v_add_f32_e32 v160, v11, v12
	s_waitcnt vmcnt(7)
	v_lshlrev_b32_e32 v8, 16, v2
	v_and_b32_e32 v2, 0xffff0000, v2
	s_waitcnt vmcnt(6)
	v_and_b32_e32 v13, 0xffff0000, v14
	v_mul_f32_e32 v2, v2, v2
	v_lshlrev_b32_e32 v9, 16, v14
	v_fmac_f32_e32 v2, v8, v8
	v_mul_f32_e32 v8, v13, v13
	v_fmac_f32_e32 v8, v9, v9
	v_lshlrev_b32_e32 v9, 16, v3
	v_and_b32_e32 v3, 0xffff0000, v3
	v_mul_f32_e32 v3, v3, v3
	v_and_b32_e32 v14, 0xffff0000, v15
	v_fmac_f32_e32 v3, v9, v9
	v_lshlrev_b32_e32 v13, 16, v15
	v_add_f32_e32 v2, v2, v3
	v_mul_f32_e32 v3, v14, v14
	v_fmac_f32_e32 v3, v13, v13
	v_add_f32_e32 v3, v8, v3
	v_lshlrev_b32_e32 v8, 16, v4
	v_and_b32_e32 v4, 0xffff0000, v4
	v_mul_f32_e32 v4, v4, v4
	v_and_b32_e32 v13, 0xffff0000, v16
	v_fmac_f32_e32 v4, v8, v8
	v_lshlrev_b32_e32 v9, 16, v16
	v_add_f32_e32 v2, v2, v4
	v_mul_f32_e32 v4, v13, v13
	v_fmac_f32_e32 v4, v9, v9
	v_add_f32_e32 v3, v3, v4
	v_lshlrev_b32_e32 v4, 16, v5
	v_and_b32_e32 v5, 0xffff0000, v5
	v_mul_f32_e32 v5, v5, v5
	v_and_b32_e32 v9, 0xffff0000, v17
	v_fmac_f32_e32 v5, v4, v4
	v_lshlrev_b32_e32 v8, 16, v17
	v_add_f32_e32 v13, v2, v5
	v_mul_f32_e32 v2, v9, v9
	v_fmac_f32_e32 v2, v8, v8
	v_add_f32_e32 v8, v3, v2
	s_waitcnt vmcnt(4)
	v_mov_b64_e32 v[2:3], v[100:101]
	v_mov_b64_e32 v[4:5], v[102:103]
	v_mov_b64_e32 v[14:15], v[104:105]
	v_mov_b64_e32 v[16:17], v[106:107]
	v_lshlrev_b32_e32 v9, 16, v2
	v_and_b32_e32 v2, 0xffff0000, v2
	v_lshlrev_b32_e32 v18, 16, v14
	v_and_b32_e32 v14, 0xffff0000, v14
	v_mul_f32_e32 v2, v2, v2
	v_fmac_f32_e32 v2, v9, v9
	v_mul_f32_e32 v9, v14, v14
	v_fmac_f32_e32 v9, v18, v18
	v_add_f32_e32 v8, v8, v9
	v_lshlrev_b32_e32 v9, 16, v3
	v_and_b32_e32 v3, 0xffff0000, v3
	v_mul_f32_e32 v3, v3, v3
	v_add_f32_e32 v2, v13, v2
	v_and_b32_e32 v14, 0xffff0000, v15
	v_fmac_f32_e32 v3, v9, v9
	v_lshlrev_b32_e32 v13, 16, v15
	v_add_f32_e32 v2, v2, v3
	v_mul_f32_e32 v3, v14, v14
	v_fmac_f32_e32 v3, v13, v13
	v_add_f32_e32 v3, v8, v3
	v_lshlrev_b32_e32 v8, 16, v4
	v_and_b32_e32 v4, 0xffff0000, v4
	v_mul_f32_e32 v4, v4, v4
	v_and_b32_e32 v13, 0xffff0000, v16
	v_fmac_f32_e32 v4, v8, v8
	v_lshlrev_b32_e32 v9, 16, v16
	v_add_f32_e32 v2, v2, v4
	v_mul_f32_e32 v4, v13, v13
	v_fmac_f32_e32 v4, v9, v9
	v_add_f32_e32 v3, v3, v4
	v_lshlrev_b32_e32 v4, 16, v5
	v_and_b32_e32 v5, 0xffff0000, v5
	v_mul_f32_e32 v5, v5, v5
	v_and_b32_e32 v9, 0xffff0000, v17
	v_fmac_f32_e32 v5, v4, v4
	v_lshlrev_b32_e32 v8, 16, v17
	v_add_f32_e32 v13, v2, v5
	v_mul_f32_e32 v2, v9, v9
	v_fmac_f32_e32 v2, v8, v8
	v_add_f32_e32 v8, v3, v2
	s_waitcnt vmcnt(2)
; #define LAS __attribute__((address_space(3)))
; __device__ __forceinline__ int lane_id_asm() { int l; asm volatile("v_mbcnt_lo_u32_b32 %0, -1, 0\n\tv_mbcnt_hi_u32_b32 %0, -1, %0" : "=v"(l)); return l; }
; template <int X> __device__ __forceinline__ float xorl(float v) { return __int_as_float(__builtin_amdgcn_ds_swizzle(__float_as_int(v), (X << 10) | 0x1f)); }
; __device__ __forceinline__ float sum32(float v) { auto rr = __builtin_amdgcn_permlane32_swap(__float_as_uint(v), __float_as_uint(v), false, false); return __uint_as_float(rr[0]) + __uint_as_float(rr[1]); }
; __global__ void __launch_bounds__(NTHREADS, 2) mega_fwd(Params p) {
;     ...
;                         for (int d0 = 0; d0 < 4; ++d0) { const u32x4 ra = *(const u32x4*)(qrow + d0 * 16 + hiq * 8), rb = *(const u32x4*)(qrow + 64 + d0 * 16 + hiq * 8);
; #pragma unroll
;                             for (int e = 0; e < 4; ++e) { const float a0 = __uint_as_float(ra[e] << 16), a1 = __uint_as_float(ra[e] & 0xffff0000u), b0 = __uint_as_float(rb[e] << 16), b1 = __uint_as_float(rb[e] & 0xffff0000u);
;                                 qa += a0 * a0 + a1 * a1; qbb += b0 * b0 + b1 * b1; } }
;                         qa = sum32(qa); qbb = sum32(qbb);
;                         float rf = __builtin_fmaxf(qa * kb2a, qbb * kb2b);
;                         rf = __builtin_fmaxf(rf, xorl<1>(rf)); rf = __builtin_fmaxf(rf, xorl<2>(rf)); rf = __builtin_fmaxf(rf, xorl<4>(rf)); rf = __builtin_fmaxf(rf, xorl<8>(rf)); rf = __builtin_fmaxf(rf, xorl<16>(rf));
;                         LAS float* slot = (LAS float*)(lds + XCH_OFF);
;                         if (lane_id_asm() == 0) slot[wave] = rf;
	v_mov_b64_e32 v[2:3], v[108:109]
	v_mov_b64_e32 v[4:5], v[110:111]
	v_mov_b64_e32 v[14:15], v[112:113]
	v_mov_b64_e32 v[16:17], v[114:115]
	v_lshlrev_b32_e32 v9, 16, v2
	v_and_b32_e32 v2, 0xffff0000, v2
	v_lshlrev_b32_e32 v18, 16, v14
	v_and_b32_e32 v14, 0xffff0000, v14
	v_mul_f32_e32 v2, v2, v2
	v_fmac_f32_e32 v2, v9, v9
	v_mul_f32_e32 v9, v14, v14
	v_fmac_f32_e32 v9, v18, v18
	v_add_f32_e32 v8, v8, v9
	v_lshlrev_b32_e32 v9, 16, v3
	v_and_b32_e32 v3, 0xffff0000, v3
	v_mul_f32_e32 v3, v3, v3
	v_add_f32_e32 v2, v13, v2
	v_and_b32_e32 v14, 0xffff0000, v15
	v_fmac_f32_e32 v3, v9, v9
	v_lshlrev_b32_e32 v13, 16, v15
	v_add_f32_e32 v2, v2, v3
	v_mul_f32_e32 v3, v14, v14
	v_fmac_f32_e32 v3, v13, v13
	v_add_f32_e32 v3, v8, v3
	v_lshlrev_b32_e32 v8, 16, v4
	v_and_b32_e32 v4, 0xffff0000, v4
	v_mul_f32_e32 v4, v4, v4
	v_and_b32_e32 v13, 0xffff0000, v16
	v_fmac_f32_e32 v4, v8, v8
	v_lshlrev_b32_e32 v9, 16, v16
	v_add_f32_e32 v2, v2, v4
	v_mul_f32_e32 v4, v13, v13
	v_fmac_f32_e32 v4, v9, v9
	v_add_f32_e32 v3, v3, v4
	v_lshlrev_b32_e32 v4, 16, v5
	v_and_b32_e32 v5, 0xffff0000, v5
	v_mul_f32_e32 v5, v5, v5
	v_and_b32_e32 v9, 0xffff0000, v17
	v_fmac_f32_e32 v5, v4, v4
	v_lshlrev_b32_e32 v8, 16, v17
	v_add_f32_e32 v14, v2, v5
	v_mul_f32_e32 v2, v9, v9
	v_fmac_f32_e32 v2, v8, v8
	v_add_f32_e32 v13, v3, v2
	s_waitcnt vmcnt(0)
	v_mov_b64_e32 v[2:3], v[116:117]
	v_mov_b64_e32 v[4:5], v[118:119]
	v_mov_b64_e32 v[6:7], v[120:121]
	v_mov_b64_e32 v[8:9], v[122:123]
	v_lshlrev_b32_e32 v15, 16, v2
	v_lshlrev_b32_e32 v16, 16, v6
	v_and_b32_e32 v6, 0xffff0000, v6
	v_mul_f32_e32 v6, v6, v6
	v_and_b32_e32 v2, 0xffff0000, v2
	v_fmac_f32_e32 v6, v16, v16
	v_mul_f32_e32 v2, v2, v2
	v_add_f32_e32 v6, v13, v6
	v_lshlrev_b32_e32 v13, 16, v3
	v_and_b32_e32 v3, 0xffff0000, v3
	v_fmac_f32_e32 v2, v15, v15
	v_mul_f32_e32 v3, v3, v3
	v_add_f32_e32 v2, v14, v2
	v_lshlrev_b32_e32 v14, 16, v7
	v_and_b32_e32 v7, 0xffff0000, v7
	v_fmac_f32_e32 v3, v13, v13
	v_add_f32_e32 v2, v2, v3
	v_mul_f32_e32 v3, v7, v7
	v_fmac_f32_e32 v3, v14, v14
	v_add_f32_e32 v3, v6, v3
	v_lshlrev_b32_e32 v6, 16, v4
	v_and_b32_e32 v4, 0xffff0000, v4
	v_mul_f32_e32 v4, v4, v4
	v_lshlrev_b32_e32 v7, 16, v8
	v_and_b32_e32 v8, 0xffff0000, v8
	v_fmac_f32_e32 v4, v6, v6
	v_add_f32_e32 v2, v2, v4
	v_mul_f32_e32 v4, v8, v8
	v_fmac_f32_e32 v4, v7, v7
	v_add_f32_e32 v3, v3, v4
	v_lshlrev_b32_e32 v4, 16, v5
	v_and_b32_e32 v5, 0xffff0000, v5
	v_mul_f32_e32 v5, v5, v5
	v_and_b32_e32 v7, 0xffff0000, v9
	v_fmac_f32_e32 v5, v4, v4
	v_lshlrev_b32_e32 v6, 16, v9
	v_add_f32_e32 v4, v2, v5
	v_mul_f32_e32 v2, v7, v7
	v_fmac_f32_e32 v2, v6, v6
	v_add_f32_e32 v3, v3, v2
	v_add_f32_e32 v2, v0, v10
	v_mov_b32_e32 v0, v4
	s_nop 1
	v_permlane32_swap_b32_e32 v4, v0
	v_add_f32_e32 v0, v4, v0
	v_mov_b32_e32 v4, v3
	s_nop 1
	v_permlane32_swap_b32_e32 v3, v4
	v_add_f32_e32 v3, v3, v4
	v_mul_f32_e32 v0, v2, v0
	v_mul_f32_e32 v3, v160, v3
	v_max_f32_e32 v0, v0, v3
	ds_swizzle_b32 v3, v0 offset:swizzle(SWAP,1)
	v_mbcnt_lo_u32_b32 v4, -1, 0
	v_mbcnt_hi_u32_b32 v4, -1, v4
	s_waitcnt lgkmcnt(0)
	v_max_f32_e32 v3, v3, v3
	v_max_f32_e32 v0, v0, v3
	ds_swizzle_b32 v3, v0 offset:swizzle(SWAP,2)
	v_cmp_eq_u32_e32 vcc, 0, v4
	s_waitcnt lgkmcnt(0)
	v_max_f32_e32 v3, v3, v3
	v_max_f32_e32 v0, v0, v3
	ds_swizzle_b32 v3, v0 offset:swizzle(SWAP,4)
	s_waitcnt lgkmcnt(0)
	v_max_f32_e32 v3, v3, v3
	v_max_f32_e32 v0, v0, v3
	ds_swizzle_b32 v3, v0 offset:swizzle(SWAP,8)
	s_waitcnt lgkmcnt(0)
	v_max_f32_e32 v3, v3, v3
	v_max_f32_e32 v0, v0, v3
	ds_swizzle_b32 v3, v0 offset:swizzle(SWAP,16)
	s_and_saveexec_b64 s[6:7], vcc
	s_cbranch_execz .LBB0_1326
	s_waitcnt lgkmcnt(0)
	v_max_f32_e32 v3, v3, v3
	v_max_f32_e32 v0, v0, v0
	v_max_f32_e32 v0, v0, v3
	v_mov_b32_e32 v3, s96
	ds_write_b32 v3, v0
